# K-loop entry vmcnt(0) also skipped for the first unit of residual phases (prologue waits already cover the residual loads)
# baseline (speedup 1.0000x reference)
.LBB0_229:
	s_mov_b32 s5, 0
	s_mov_b64 s[12:13], 0x100
	v_mov_b64_e32 v[2:3], v[156:157]
	v_mov_b64_e32 v[132:133], v[154:155]
	s_cmp_lg_u32 s84, 0
	s_cbranch_scc1 .Lkl_nowait
	s_cmp_eq_u32 s67, 0
	s_cbranch_scc1 .Lkl_nowait
	s_waitcnt vmcnt(0)
